# LayerNorm wave reductions: xor-1/2/4/8 butterfly steps via DPP adds instead of ds_bpermute round trips
# speedup vs baseline: 1.0145x; 1.0017x over previous
; __device__ __forceinline__ float wave_sum(float v) {
; #pragma unroll
;     for (int o = 1; o < 64; o <<= 1) v += __shfl_xor(v, o);
;     return v;
; }
; __global__ void __launch_bounds__(512, 2) mk_fwd(Args args) {
;     ...
;                 auto ln_row = [&](const int row, f32x4 (&v)[4]) __attribute__((always_inline)) {
;                     const bool lat = row < ML;
;                     float* xr = lat ? XL + (size_t)row * DM : XC + (size_t)(row - ML) * DM;
;                     const float* mp = mp0 + (size_t)(lat ? (row >> 11) : 16) * 6144;
;                     float s = 0.f;
; #pragma unroll
;                     for (int j = 0; j < 4; ++j) s += (v[j][0] + v[j][1]) + (v[j][2] + v[j][3]);
;                     const float mean = wave_sum(s) * (1.0f / DM); float s2 = 0.f;
; #pragma unroll
;                     for (int j = 0; j < 4; ++j) { v[j] = v[j] - mean; s2 += (v[j][0] * v[j][0] + v[j][1] * v[j][1]) + (v[j][2] * v[j][2] + v[j][3] * v[j][3]); }
;                     const float rstd = 1.0f / sqrtf(wave_sum(s2) * (1.0f / DM) + LN_EPS);
;                     if (lane == 0) { STAT[2 * (size_t)row] = mean; STAT[2 * (size_t)row + 1] = rstd; }
.LBB0_822:
	s_waitcnt vmcnt(0) lgkmcnt(0)
	v_mov_b32_e32 v56, v31
	v_mov_b32_e32 v57, v32
	v_mov_b32_e32 v58, v30
	v_mov_b32_e32 v59, v33
	v_pk_add_f32 v[56:57], v[56:57], v[58:59]
	v_mov_b32_e32 v58, v27
	v_mov_b32_e32 v59, v28
	v_mov_b32_e32 v62, v26
	v_mov_b32_e32 v63, v29
	v_pk_add_f32 v[58:59], v[58:59], v[62:63]
	v_add_f32_e32 v56, v56, v57
	v_pk_add_f32 v[58:59], v[58:59], v[58:59] op_sel_hi:[0,1]
	v_add_f32_e32 v57, 0, v56
	v_add_f32_e32 v63, v22, v23
	v_add_f32_e32 v65, v24, v25
	v_mov_b32_e32 v62, v18
	v_mov_b32_e32 v64, v19
	v_mov_b32_e32 v58, v20
	v_mov_b32_e32 v56, v21
	v_pk_add_f32 v[62:63], v[62:63], v[64:65]
	v_pk_add_f32 v[56:57], v[58:59], v[56:57]
	s_nop 0
	v_pk_add_f32 v[56:57], v[62:63], v[56:57]
	s_nop 0
	v_add_f32_e32 v56, v56, v57
	s_nop 1
	v_add_f32_dpp v56, v56, v56 quad_perm:[1,0,3,2] row_mask:0xf bank_mask:0xf
	s_nop 1
	v_add_f32_dpp v56, v56, v56 quad_perm:[2,3,0,1] row_mask:0xf bank_mask:0xf
	s_nop 1
	v_add_f32_dpp v56, v56, v56 row_half_mirror row_mask:0xf bank_mask:0xf
	s_nop 1
	v_add_f32_dpp v56, v56, v56 row_mirror row_mask:0xf bank_mask:0xf
	ds_bpermute_b32 v57, v60, v56
	s_waitcnt lgkmcnt(0)
	v_add_f32_e32 v56, v56, v57
	ds_bpermute_b32 v57, v61, v56
	s_waitcnt lgkmcnt(0)
	v_add_f32_e32 v57, v56, v57
	v_fmamk_f32 v33, v57, 0xba800000, v33
	v_fmamk_f32 v31, v57, 0xba800000, v31
	v_fmamk_f32 v32, v57, 0xba800000, v32
	v_fmac_f32_e32 v30, 0xba800000, v57
	v_mul_f32_e32 v56, v31, v31
	v_mul_f32_e32 v58, v33, v33
	v_fmamk_f32 v29, v57, 0xba800000, v29
	v_fmamk_f32 v27, v57, 0xba800000, v27
	v_fmac_f32_e32 v56, v30, v30
	v_fmac_f32_e32 v58, v32, v32
	v_fmamk_f32 v28, v57, 0xba800000, v28
	v_add_f32_e32 v56, v56, v58
	v_fmac_f32_e32 v26, 0xba800000, v57
	v_mul_f32_e32 v58, v27, v27
	v_mul_f32_e32 v59, v29, v29
	v_fmac_f32_e32 v58, v26, v26
	v_fmac_f32_e32 v59, v28, v28
	v_add_f32_e32 v58, v58, v59
	v_fmamk_f32 v25, v57, 0xba800000, v25
	v_fmamk_f32 v23, v57, 0xba800000, v23
	v_add_f32_e32 v56, v56, v58
	v_fmamk_f32 v24, v57, 0xba800000, v24
	v_fmac_f32_e32 v22, 0xba800000, v57
	v_mul_f32_e32 v58, v23, v23
	v_mul_f32_e32 v59, v25, v25
	v_fmac_f32_e32 v58, v22, v22
	v_fmac_f32_e32 v59, v24, v24
	v_add_f32_e32 v58, v58, v59
	v_fmamk_f32 v21, v57, 0xba800000, v21
	v_fmamk_f32 v19, v57, 0xba800000, v19
	v_add_f32_e32 v56, v58, v56
	v_fmamk_f32 v20, v57, 0xba800000, v20
	v_fmac_f32_e32 v18, 0xba800000, v57
	v_mul_f32_e32 v58, v19, v19
	v_mul_f32_e32 v59, v21, v21
	v_fmac_f32_e32 v58, v18, v18
	v_fmac_f32_e32 v59, v20, v20
	v_add_f32_e32 v58, v58, v59
	v_add_f32_e32 v56, v58, v56
	s_nop 1
	v_add_f32_dpp v56, v56, v56 quad_perm:[1,0,3,2] row_mask:0xf bank_mask:0xf
	s_nop 1
	v_add_f32_dpp v56, v56, v56 quad_perm:[2,3,0,1] row_mask:0xf bank_mask:0xf
	s_nop 1
	v_add_f32_dpp v56, v56, v56 row_half_mirror row_mask:0xf bank_mask:0xf
	s_nop 1
	v_add_f32_dpp v56, v56, v56 row_mirror row_mask:0xf bank_mask:0xf
	ds_bpermute_b32 v58, v60, v56
	s_waitcnt lgkmcnt(0)
	v_add_f32_e32 v56, v56, v58
	ds_bpermute_b32 v58, v61, v56
	s_waitcnt lgkmcnt(0)
	v_add_f32_e32 v56, v56, v58
	v_fmamk_f32 v56, v56, 0x3a800000, v228
	v_mul_f32_e32 v58, 0x4f800000, v56
	v_cmp_gt_f32_e32 vcc, s28, v56
	s_nop 1
	v_cndmask_b32_e32 v56, v56, v58, vcc
	v_sqrt_f32_e32 v58, v56
	s_nop 0
	v_add_u32_e32 v59, -1, v58
	v_fma_f32 v63, -v59, v58, v56
	v_add_u32_e32 v62, 1, v58
	v_cmp_ge_f32_e64 s[4:5], 0, v63
	s_nop 1
	v_cndmask_b32_e64 v59, v58, v59, s[4:5]
	v_fma_f32 v58, -v62, v58, v56
	v_cmp_lt_f32_e64 s[4:5], 0, v58
	s_nop 1
	v_cndmask_b32_e64 v58, v59, v62, s[4:5]
	v_mul_f32_e32 v59, 0x37800000, v58
	v_cndmask_b32_e32 v58, v58, v59, vcc
	v_cmp_class_f32_e32 vcc, v56, v238
	s_nop 1
	v_cndmask_b32_e32 v56, v58, v56, vcc
	v_div_scale_f32 v58, s[4:5], v56, v56, 1.0
	v_rcp_f32_e32 v59, v58
	s_nop 0
	v_fma_f32 v62, -v58, v59, 1.0
	v_fmac_f32_e32 v59, v62, v59
	v_div_scale_f32 v62, vcc, 1.0, v56, 1.0
	v_mul_f32_e32 v63, v62, v59
	v_fma_f32 v64, -v58, v63, v62
	v_fmac_f32_e32 v63, v64, v59
	v_fma_f32 v58, -v58, v63, v62
	v_div_fmas_f32 v58, v58, v59, v63
	v_div_fixup_f32 v56, v58, v56, 1.0
	s_and_saveexec_b64 s[4:5], s[0:1]
	s_cbranch_execz .LBB0_824
	v_readlane_b32 s18, v254, 36
	v_readlane_b32 s19, v254, 37
	s_add_u32 s18, s18, s15
	s_addc_u32 s19, s19, s16
	v_mul_f32_e32 v58, 0x3a800000, v57
	v_mov_b32_e32 v59, v56
	v_mov_b64_e32 v[62:63], s[18:19]
	flat_store_dwordx2 v[62:63], v[58:59]

; __device__ __forceinline__ float wave_sum(float v) {
; #pragma unroll
;     for (int o = 1; o < 64; o <<= 1) v += __shfl_xor(v, o);
;     return v;
; }
; __global__ void __launch_bounds__(512, 2) mk_fwd(Args args) {
;     ...
;                 auto ln_row = [&](const int row, f32x4 (&v)[4]) __attribute__((always_inline)) {
;                     const bool lat = row < ML;
;                     float* xr = lat ? XL + (size_t)row * DM : XC + (size_t)(row - ML) * DM;
;                     const float* mp = mp0 + (size_t)(lat ? (row >> 11) : 16) * 6144;
;                     float s = 0.f;
; #pragma unroll
;                     for (int j = 0; j < 4; ++j) s += (v[j][0] + v[j][1]) + (v[j][2] + v[j][3]);
;                     const float mean = wave_sum(s) * (1.0f / DM); float s2 = 0.f;
; #pragma unroll
;                     for (int j = 0; j < 4; ++j) { v[j] = v[j] - mean; s2 += (v[j][0] * v[j][0] + v[j][1] * v[j][1]) + (v[j][2] * v[j][2] + v[j][3] * v[j][3]); }
;                     const float rstd = 1.0f / sqrtf(wave_sum(s2) * (1.0f / DM) + LN_EPS);
;                     if (lane == 0) { STAT[2 * (size_t)row] = mean; STAT[2 * (size_t)row + 1] = rstd; }
.LBB0_841:
	v_mov_b32_e32 v18, v11
	v_mov_b32_e32 v19, v12
	v_mov_b32_e32 v20, v10
	v_mov_b32_e32 v21, v13
	v_pk_add_f32 v[18:19], v[18:19], v[20:21]
	v_mov_b32_e32 v20, v7
	v_mov_b32_e32 v21, v8
	v_mov_b32_e32 v22, v6
	v_mov_b32_e32 v23, v9
	v_pk_add_f32 v[20:21], v[20:21], v[22:23]
	v_add_f32_e32 v18, v18, v19
	v_pk_add_f32 v[20:21], v[20:21], v[20:21] op_sel_hi:[0,1]
	v_add_f32_e32 v19, 0, v18
	v_add_f32_e32 v23, v2, v3
	v_add_f32_e32 v25, v4, v5
	v_mov_b32_e32 v22, v14
	v_mov_b32_e32 v24, v15
	v_mov_b32_e32 v20, v16
	v_mov_b32_e32 v18, v17
	v_pk_add_f32 v[14:15], v[22:23], v[24:25]
	v_pk_add_f32 v[16:17], v[20:21], v[18:19]
	s_ashr_i32 s91, s90, 31
	v_pk_add_f32 v[14:15], v[14:15], v[16:17]
	s_nop 0
	v_add_f32_e32 v14, v14, v15
	s_nop 1
	v_add_f32_dpp v14, v14, v14 quad_perm:[1,0,3,2] row_mask:0xf bank_mask:0xf
	s_nop 1
	v_add_f32_dpp v14, v14, v14 quad_perm:[2,3,0,1] row_mask:0xf bank_mask:0xf
	s_nop 1
	v_add_f32_dpp v14, v14, v14 row_half_mirror row_mask:0xf bank_mask:0xf
	s_nop 1
	v_add_f32_dpp v14, v14, v14 row_mirror row_mask:0xf bank_mask:0xf
	ds_bpermute_b32 v15, v60, v14
	s_waitcnt lgkmcnt(0)
	v_add_f32_e32 v14, v14, v15
	ds_bpermute_b32 v15, v61, v14
	s_waitcnt lgkmcnt(0)
	v_add_f32_e32 v15, v14, v15
	v_fmac_f32_e32 v13, 0xba800000, v15
	v_fmac_f32_e32 v11, 0xba800000, v15
	v_fmac_f32_e32 v12, 0xba800000, v15
	v_fmac_f32_e32 v10, 0xba800000, v15
	v_mul_f32_e32 v14, v11, v11
	v_mul_f32_e32 v16, v13, v13
	v_fmac_f32_e32 v9, 0xba800000, v15
	v_fmac_f32_e32 v7, 0xba800000, v15
	v_fmac_f32_e32 v14, v10, v10
	v_fmac_f32_e32 v16, v12, v12
	v_fmac_f32_e32 v8, 0xba800000, v15
	v_add_f32_e32 v14, v14, v16
	v_fmac_f32_e32 v6, 0xba800000, v15
	v_mul_f32_e32 v16, v7, v7
	v_mul_f32_e32 v17, v9, v9
	v_fmac_f32_e32 v16, v6, v6
	v_fmac_f32_e32 v17, v8, v8
	v_add_f32_e32 v16, v16, v17
	v_fmac_f32_e32 v5, 0xba800000, v15
	v_fmac_f32_e32 v3, 0xba800000, v15
	v_add_f32_e32 v14, v14, v16
	v_fmac_f32_e32 v4, 0xba800000, v15
	v_fmac_f32_e32 v2, 0xba800000, v15
	v_mul_f32_e32 v16, v3, v3
	v_mul_f32_e32 v17, v5, v5
	v_fmac_f32_e32 v16, v2, v2
	v_fmac_f32_e32 v17, v4, v4
	v_add_f32_e32 v16, v16, v17
	v_fmac_f32_e32 v53, 0xba800000, v15
	v_fmac_f32_e32 v55, 0xba800000, v15
	v_add_f32_e32 v14, v16, v14
	v_fmac_f32_e32 v52, 0xba800000, v15
	v_fmac_f32_e32 v54, 0xba800000, v15
	v_mul_f32_e32 v16, v55, v55
	v_mul_f32_e32 v17, v53, v53
	v_fmac_f32_e32 v16, v54, v54
	v_fmac_f32_e32 v17, v52, v52
	v_add_f32_e32 v16, v16, v17
	v_add_f32_e32 v14, v16, v14
	s_nop 1
	v_add_f32_dpp v14, v14, v14 quad_perm:[1,0,3,2] row_mask:0xf bank_mask:0xf
	s_nop 1
	v_add_f32_dpp v14, v14, v14 quad_perm:[2,3,0,1] row_mask:0xf bank_mask:0xf
	s_nop 1
	v_add_f32_dpp v14, v14, v14 row_half_mirror row_mask:0xf bank_mask:0xf
	s_nop 1
	v_add_f32_dpp v14, v14, v14 row_mirror row_mask:0xf bank_mask:0xf
	ds_bpermute_b32 v16, v60, v14
	s_waitcnt lgkmcnt(0)
	v_add_f32_e32 v14, v14, v16
	ds_bpermute_b32 v16, v61, v14
	s_waitcnt lgkmcnt(0)
	v_add_f32_e32 v14, v14, v16
	v_fmamk_f32 v14, v14, 0x3a800000, v228
	v_mul_f32_e32 v16, 0x4f800000, v14
	v_cmp_gt_f32_e32 vcc, s28, v14
	s_nop 1
	v_cndmask_b32_e32 v14, v14, v16, vcc
	v_sqrt_f32_e32 v16, v14
	s_nop 0
	v_add_u32_e32 v17, -1, v16
	v_fma_f32 v19, -v17, v16, v14
	v_add_u32_e32 v18, 1, v16
	v_cmp_ge_f32_e64 s[4:5], 0, v19
	s_nop 1
	v_cndmask_b32_e64 v17, v16, v17, s[4:5]
	v_fma_f32 v16, -v18, v16, v14
	v_cmp_lt_f32_e64 s[4:5], 0, v16
	s_nop 1
	v_cndmask_b32_e64 v16, v17, v18, s[4:5]
	v_mul_f32_e32 v17, 0x37800000, v16
	v_cndmask_b32_e32 v16, v16, v17, vcc
	v_cmp_class_f32_e32 vcc, v14, v238
	s_nop 1
	v_cndmask_b32_e32 v14, v16, v14, vcc
	v_div_scale_f32 v16, s[4:5], v14, v14, 1.0
	v_rcp_f32_e32 v17, v16
	s_nop 0
	v_fma_f32 v18, -v16, v17, 1.0
	v_fmac_f32_e32 v17, v18, v17
	v_div_scale_f32 v18, vcc, 1.0, v14, 1.0
	v_mul_f32_e32 v19, v18, v17
	v_fma_f32 v20, -v16, v19, v18
	v_fmac_f32_e32 v19, v20, v17
	v_fma_f32 v16, -v16, v19, v18
	v_div_fmas_f32 v16, v16, v17, v19
	v_div_fixup_f32 v14, v16, v14, 1.0
	s_and_saveexec_b64 s[4:5], s[0:1]
	s_cbranch_execz .LBB0_843
	s_lshl_b64 s[18:19], s[90:91], 3
	s_add_u32 s18, s42, s18
	s_addc_u32 s19, s43, s19
	v_mul_f32_e32 v16, 0x3a800000, v15
	v_mov_b32_e32 v17, v14
	v_mov_b64_e32 v[18:19], s[18:19]
	flat_store_dwordx2 v[18:19], v[16:17]
